# l1 lora-up GEMM epilogues: bias vectors loaded once per unit ahead of the epilogue (was a load + full vmcnt drain, behind the previous store, per accumulator tile)
# speedup vs baseline: 1.0207x; 1.0014x over previous
.LBB0_2759:
	s_mul_hi_i32 s23, s12, 0x2aaaaaab
	s_lshr_b32 s24, s23, 31
	s_ashr_i32 s23, s23, 3
	s_add_i32 s23, s23, s24
	s_mul_i32 s25, s23, 0xffffe800
	s_lshl_b32 s24, s23, 7
	s_add_i32 s26, s17, s25
	s_ashr_i32 s25, s24, 31
	s_ashr_i32 s27, s26, 31
	v_or_b32_e32 v22, s24, v43
	s_lshl_b64 s[24:25], s[24:25], 7
	v_add_u32_e32 v36, s26, v44
	s_lshl_b64 s[26:27], s[26:27], 8
	s_add_u32 s26, s13, s26
	s_addc_u32 s27, s14, s27
	s_add_u32 s24, s15, s24
	v_lshl_add_u64 v[2:3], s[26:27], 0, v[26:27]
	s_mov_b32 m0, s19
	v_lshl_add_u64 v[4:5], s[26:27], 0, v[28:29]
	s_addc_u32 s25, s16, s25
	v_lshl_add_u64 v[2:3], v[2:3], 0, v[34:35]
	v_lshl_add_u64 v[4:5], v[4:5], 0, v[34:35]
	global_load_lds_dwordx4 v[2:3], off
	v_lshl_add_u64 v[2:3], s[24:25], 0, v[30:31]
	s_mov_b32 m0, s20
	v_lshl_add_u64 v[6:7], s[24:25], 0, v[32:33]
	global_load_lds_dwordx4 v[4:5], off
	v_lshl_add_u64 v[2:3], v[2:3], 0, v[34:35]
	s_mov_b32 m0, s21
	v_lshl_add_u64 v[4:5], v[6:7], 0, v[34:35]
	global_load_lds_dwordx4 v[2:3], off
	s_mov_b32 m0, s22
	v_ashrrev_i32_e32 v23, 31, v22
	global_load_lds_dwordx4 v[4:5], off
	s_waitcnt vmcnt(0)
	s_barrier
	ds_read_b128 v[18:21], v46 offset:17408
	ds_read_b128 v[14:17], v45 offset:1024
	ds_read_b128 v[48:51], v45 offset:2048
	ds_read_b128 v[6:9], v46 offset:18432
	ds_read_b128 v[10:13], v46 offset:19456
	ds_read_b128 v[2:5], v46 offset:20480
	s_waitcnt lgkmcnt(0)
	v_mfma_f32_16x16x32_bf16 v[52:55], v[18:21], v[14:17], 0
	v_lshlrev_b64 v[38:39], 2, v[22:23]
	v_lshl_add_u64 v[40:41], s[2:3], 0, v[38:39]
	global_load_dwordx4 v[200:203], v[40:41], off
	global_load_dwordx4 v[204:207], v[40:41], off offset:64
	v_ashrrev_i32_e32 v37, 31, v36
	v_mfma_f32_16x16x32_bf16 v[56:59], v[10:13], v[14:17], 0
	ds_read_b128 v[14:17], v45 offset:3072
	ds_read_b128 v[60:63], v45 offset:4096
	v_lshlrev_b64 v[88:89], 11, v[36:37]
	v_lshl_add_u64 v[88:89], s[4:5], 0, v[88:89]
	s_waitcnt lgkmcnt(0)
	v_mfma_f32_16x16x32_bf16 v[64:67], v[18:21], v[14:17], 0
	v_lshl_add_u64 v[88:89], v[88:89], 0, v[38:39]
	v_add_u32_e32 v84, 16, v36
	v_ashrrev_i32_e32 v85, 31, v84
	v_mfma_f32_16x16x32_bf16 v[68:71], v[10:13], v[14:17], 0
	ds_read_b128 v[14:17], v45 offset:5120
	ds_read_b128 v[72:75], v45 offset:6144
	v_lshlrev_b64 v[84:85], 11, v[84:85]
	v_lshl_add_u64 v[84:85], s[4:5], 0, v[84:85]
	s_waitcnt lgkmcnt(0)
	v_mfma_f32_16x16x32_bf16 v[76:79], v[18:21], v[14:17], 0
	v_lshl_add_u64 v[84:85], v[84:85], 0, v[38:39]
	v_add_u32_e32 v86, 32, v36
	v_ashrrev_i32_e32 v87, 31, v86
	v_mfma_f32_16x16x32_bf16 v[80:83], v[10:13], v[14:17], 0
	ds_read_b128 v[22:25], v45 offset:7168
	ds_read_b128 v[14:17], v45 offset:8192
	s_waitcnt lgkmcnt(0)
	s_barrier
	v_mfma_f32_16x16x32_bf16 v[52:55], v[6:9], v[48:51], v[52:55]
	v_add_u32_e32 v36, 48, v36
	s_add_i32 s12, s12, s56
	s_add_i32 s17, s17, s18
	v_mfma_f32_16x16x32_bf16 v[48:51], v[2:5], v[48:51], v[56:59]
	s_cmpk_lt_i32 s12, 0xc0
	v_mfma_f32_16x16x32_bf16 v[56:59], v[6:9], v[60:63], v[64:67]
	s_nop 2
	s_waitcnt vmcnt(0)
	s_nop 1
	v_mov_b64_e32 v[64:65], v[200:201]
	v_mov_b64_e32 v[66:67], v[202:203]
	v_mfma_f32_16x16x32_bf16 v[60:63], v[2:5], v[60:63], v[68:71]
	s_nop 0
	v_add_f32_e32 v37, v52, v64
	v_add_f32_e32 v47, v53, v65
	v_add_f32_e32 v52, v54, v66
	v_add_f32_e32 v53, v55, v67
	v_mul_f32_e32 v37, 0xbfb8aa3b, v37
	v_mul_f32_e32 v47, 0xbfb8aa3b, v47
	v_mul_f32_e32 v52, 0xbfb8aa3b, v52
	v_mul_f32_e32 v53, 0xbfb8aa3b, v53
	v_exp_f32_e32 v37, v37
	v_exp_f32_e32 v47, v47
	v_exp_f32_e32 v52, v52
	v_exp_f32_e32 v53, v53
	v_add_f32_e32 v37, 1.0, v37
	v_add_f32_e32 v47, 1.0, v47
	v_add_f32_e32 v52, 1.0, v52
	v_add_f32_e32 v53, 1.0, v53
	v_rcp_f32_e32 v37, v37
	v_rcp_f32_e32 v47, v47
	v_rcp_f32_e32 v52, v52
	v_rcp_f32_e32 v53, v53
	v_mul_f32_e32 v37, 0xbf1b4598, v37
	v_mul_f32_e32 v47, 0xbf1b4598, v47
	v_mul_f32_e32 v52, 0xbf1b4598, v52
	v_mul_f32_e32 v53, 0xbf1b4598, v53
	v_mul_f32_e32 v37, 0x3fb8aa3b, v37
	v_mul_f32_e32 v47, 0x3fb8aa3b, v47
	v_mul_f32_e32 v54, 0x3fb8aa3b, v52
	v_mul_f32_e32 v55, 0x3fb8aa3b, v53
	v_exp_f32_e32 v52, v37
	v_exp_f32_e32 v53, v47
	v_exp_f32_e32 v54, v54
	v_exp_f32_e32 v55, v55
	s_waitcnt lgkmcnt(1)
	v_mfma_f32_16x16x32_bf16 v[18:21], v[18:21], v[22:25], 0
	global_store_dwordx4 v[88:89], v[52:55], off
	s_nop 1
	v_mov_b64_e32 v[52:53], v[204:205]
	v_mov_b64_e32 v[54:55], v[206:207]
	v_mfma_f32_16x16x32_bf16 v[10:13], v[10:13], v[22:25], 0
	s_nop 0
	v_add_f32_e32 v37, v48, v52
	v_add_f32_e32 v47, v49, v53
	v_add_f32_e32 v48, v50, v54
	v_add_f32_e32 v49, v51, v55
	v_mul_f32_e32 v37, 0xbfb8aa3b, v37
	v_mul_f32_e32 v47, 0xbfb8aa3b, v47
	v_mul_f32_e32 v48, 0xbfb8aa3b, v48
	v_mul_f32_e32 v49, 0xbfb8aa3b, v49
	v_exp_f32_e32 v37, v37
	v_exp_f32_e32 v47, v47
	v_exp_f32_e32 v48, v48
	v_exp_f32_e32 v49, v49
	v_add_f32_e32 v37, 1.0, v37
	v_add_f32_e32 v47, 1.0, v47
	v_add_f32_e32 v48, 1.0, v48
	v_add_f32_e32 v49, 1.0, v49
	v_rcp_f32_e32 v37, v37
	v_rcp_f32_e32 v47, v47
	v_rcp_f32_e32 v48, v48
	v_rcp_f32_e32 v49, v49
	v_mul_f32_e32 v37, 0xbf1b4598, v37
	v_mul_f32_e32 v47, 0xbf1b4598, v47
	v_mul_f32_e32 v48, 0xbf1b4598, v48
	v_mul_f32_e32 v49, 0xbf1b4598, v49
	v_mul_f32_e32 v37, 0x3fb8aa3b, v37
	v_mul_f32_e32 v47, 0x3fb8aa3b, v47
	v_mul_f32_e32 v50, 0x3fb8aa3b, v48
	v_mul_f32_e32 v51, 0x3fb8aa3b, v49
	v_exp_f32_e32 v48, v37
	v_exp_f32_e32 v49, v47
	v_exp_f32_e32 v50, v50
	v_exp_f32_e32 v51, v51
	v_lshlrev_b64 v[52:53], 11, v[86:87]
	v_lshl_add_u64 v[52:53], s[4:5], 0, v[52:53]
	global_store_dwordx4 v[88:89], v[48:51], off offset:64
	s_nop 1
	v_mov_b64_e32 v[48:49], v[200:201]
	v_mov_b64_e32 v[50:51], v[202:203]
	s_nop 0
	v_add_f32_e32 v37, v56, v48
	v_add_f32_e32 v47, v57, v49
	v_add_f32_e32 v48, v58, v50
	v_add_f32_e32 v49, v59, v51
	v_mul_f32_e32 v37, 0xbfb8aa3b, v37
	v_mul_f32_e32 v47, 0xbfb8aa3b, v47
	v_mul_f32_e32 v48, 0xbfb8aa3b, v48
	v_mul_f32_e32 v49, 0xbfb8aa3b, v49
	v_exp_f32_e32 v37, v37
	v_exp_f32_e32 v47, v47
	v_exp_f32_e32 v48, v48
	v_exp_f32_e32 v49, v49
	v_add_f32_e32 v37, 1.0, v37
	v_add_f32_e32 v47, 1.0, v47
	v_add_f32_e32 v48, 1.0, v48
	v_add_f32_e32 v49, 1.0, v49
	v_rcp_f32_e32 v37, v37
	v_rcp_f32_e32 v47, v47
	v_rcp_f32_e32 v48, v48
	v_rcp_f32_e32 v49, v49
	v_mul_f32_e32 v37, 0xbf1b4598, v37
	v_mul_f32_e32 v47, 0xbf1b4598, v47
	v_mul_f32_e32 v48, 0xbf1b4598, v48
	v_mul_f32_e32 v49, 0xbf1b4598, v49
	v_mul_f32_e32 v37, 0x3fb8aa3b, v37
	v_mul_f32_e32 v47, 0x3fb8aa3b, v47
	v_mul_f32_e32 v50, 0x3fb8aa3b, v48
	v_mul_f32_e32 v51, 0x3fb8aa3b, v49
	v_exp_f32_e32 v48, v37
	v_exp_f32_e32 v49, v47
	v_exp_f32_e32 v50, v50
	v_exp_f32_e32 v51, v51
	v_lshl_add_u64 v[56:57], v[52:53], 0, v[38:39]
	v_mfma_f32_16x16x32_bf16 v[52:55], v[6:9], v[72:75], v[76:79]
	global_store_dwordx4 v[84:85], v[48:51], off
	s_nop 1
	v_mov_b64_e32 v[48:49], v[204:205]
	v_mov_b64_e32 v[50:51], v[206:207]
	s_waitcnt lgkmcnt(0)
	v_mfma_f32_16x16x32_bf16 v[6:9], v[6:9], v[14:17], v[18:21]
	s_nop 0
	v_add_f32_e32 v37, v60, v48
	v_add_f32_e32 v47, v61, v49
	v_add_f32_e32 v48, v62, v50
	v_add_f32_e32 v49, v63, v51
	v_mul_f32_e32 v37, 0xbfb8aa3b, v37
	v_mul_f32_e32 v47, 0xbfb8aa3b, v47
	v_mul_f32_e32 v48, 0xbfb8aa3b, v48
	v_mul_f32_e32 v49, 0xbfb8aa3b, v49
	v_exp_f32_e32 v37, v37
	v_exp_f32_e32 v47, v47
	v_exp_f32_e32 v48, v48
	v_exp_f32_e32 v49, v49
	v_add_f32_e32 v37, 1.0, v37
	v_add_f32_e32 v47, 1.0, v47
	v_add_f32_e32 v48, 1.0, v48
	v_add_f32_e32 v49, 1.0, v49
	v_rcp_f32_e32 v37, v37
	v_rcp_f32_e32 v47, v47
	v_rcp_f32_e32 v48, v48
	v_rcp_f32_e32 v49, v49
	v_mul_f32_e32 v37, 0xbf1b4598, v37
	v_mul_f32_e32 v47, 0xbf1b4598, v47
	v_mul_f32_e32 v48, 0xbf1b4598, v48
	v_mul_f32_e32 v49, 0xbf1b4598, v49
	v_mul_f32_e32 v37, 0x3fb8aa3b, v37
	v_mul_f32_e32 v47, 0x3fb8aa3b, v47
	v_mul_f32_e32 v50, 0x3fb8aa3b, v48
	v_mul_f32_e32 v51, 0x3fb8aa3b, v49
	v_exp_f32_e32 v48, v37
	v_exp_f32_e32 v49, v47
	v_exp_f32_e32 v50, v50
	v_exp_f32_e32 v51, v51
	global_store_dwordx4 v[84:85], v[48:51], off offset:64
	s_nop 1
	v_mov_b64_e32 v[48:49], v[200:201]
	v_mov_b64_e32 v[50:51], v[202:203]
	s_nop 0
	v_add_f32_e32 v37, v52, v48
	v_add_f32_e32 v47, v53, v49
	v_add_f32_e32 v48, v54, v50
	v_add_f32_e32 v49, v55, v51
	v_mul_f32_e32 v37, 0xbfb8aa3b, v37
	v_mul_f32_e32 v47, 0xbfb8aa3b, v47
	v_mul_f32_e32 v48, 0xbfb8aa3b, v48
	v_mul_f32_e32 v49, 0xbfb8aa3b, v49
	v_exp_f32_e32 v37, v37
	v_exp_f32_e32 v47, v47
	v_exp_f32_e32 v48, v48
	v_exp_f32_e32 v49, v49
	v_add_f32_e32 v37, 1.0, v37
	v_add_f32_e32 v47, 1.0, v47
	v_add_f32_e32 v48, 1.0, v48
	v_add_f32_e32 v49, 1.0, v49
	v_rcp_f32_e32 v37, v37
	v_rcp_f32_e32 v47, v47
	v_rcp_f32_e32 v48, v48
	v_rcp_f32_e32 v49, v49
	v_mul_f32_e32 v37, 0xbf1b4598, v37
	v_mul_f32_e32 v47, 0xbf1b4598, v47
	v_mul_f32_e32 v48, 0xbf1b4598, v48
	v_mul_f32_e32 v49, 0xbf1b4598, v49
	v_mul_f32_e32 v37, 0x3fb8aa3b, v37
	v_mul_f32_e32 v47, 0x3fb8aa3b, v47
	v_mul_f32_e32 v50, 0x3fb8aa3b, v48
	v_mul_f32_e32 v51, 0x3fb8aa3b, v49
	v_exp_f32_e32 v48, v37
	v_exp_f32_e32 v49, v47
	v_exp_f32_e32 v50, v50
	v_exp_f32_e32 v51, v51
	v_mfma_f32_16x16x32_bf16 v[52:55], v[2:5], v[72:75], v[80:83]
	global_store_dwordx4 v[56:57], v[48:51], off
	s_nop 1
	v_mov_b64_e32 v[48:49], v[204:205]
	v_mov_b64_e32 v[50:51], v[206:207]
	v_mfma_f32_16x16x32_bf16 v[2:5], v[2:5], v[14:17], v[10:13]
	s_nop 0
	s_nop 3
	v_add_f32_e32 v37, v52, v48
	v_add_f32_e32 v47, v53, v49
	v_add_f32_e32 v48, v54, v50
	v_add_f32_e32 v49, v55, v51
	v_mul_f32_e32 v37, 0xbfb8aa3b, v37
	v_mul_f32_e32 v47, 0xbfb8aa3b, v47
	v_mul_f32_e32 v48, 0xbfb8aa3b, v48
	v_mul_f32_e32 v49, 0xbfb8aa3b, v49
	v_exp_f32_e32 v37, v37
	v_exp_f32_e32 v47, v47
	v_exp_f32_e32 v48, v48
	v_exp_f32_e32 v49, v49
	v_add_f32_e32 v37, 1.0, v37
	v_add_f32_e32 v47, 1.0, v47
	v_add_f32_e32 v48, 1.0, v48
	v_add_f32_e32 v49, 1.0, v49
	v_rcp_f32_e32 v37, v37
	v_rcp_f32_e32 v47, v47
	v_rcp_f32_e32 v48, v48
	v_rcp_f32_e32 v49, v49
	v_mul_f32_e32 v37, 0xbf1b4598, v37
	v_mul_f32_e32 v47, 0xbf1b4598, v47
	v_mul_f32_e32 v48, 0xbf1b4598, v48
	v_mul_f32_e32 v49, 0xbf1b4598, v49
	v_mul_f32_e32 v37, 0x3fb8aa3b, v37
	v_mul_f32_e32 v47, 0x3fb8aa3b, v47
	v_mul_f32_e32 v50, 0x3fb8aa3b, v48
	v_mul_f32_e32 v51, 0x3fb8aa3b, v49
	v_exp_f32_e32 v48, v37
	v_exp_f32_e32 v49, v47
	v_exp_f32_e32 v50, v50
	v_exp_f32_e32 v51, v51
	v_ashrrev_i32_e32 v37, 31, v36
	v_lshlrev_b64 v[22:23], 11, v[36:37]
	v_lshl_add_u64 v[22:23], s[4:5], 0, v[22:23]
	global_store_dwordx4 v[56:57], v[48:51], off offset:64
	s_nop 1
	v_mov_b64_e32 v[48:49], v[200:201]
	v_mov_b64_e32 v[50:51], v[202:203]
	v_lshl_add_u64 v[22:23], v[22:23], 0, v[38:39]
	s_nop 0
	v_add_f32_e32 v6, v6, v48
	v_add_f32_e32 v7, v7, v49
	v_add_f32_e32 v8, v8, v50
	v_add_f32_e32 v9, v9, v51
	v_mul_f32_e32 v6, 0xbfb8aa3b, v6
	v_mul_f32_e32 v7, 0xbfb8aa3b, v7
	v_mul_f32_e32 v8, 0xbfb8aa3b, v8
	v_mul_f32_e32 v9, 0xbfb8aa3b, v9
	v_exp_f32_e32 v6, v6
	v_exp_f32_e32 v7, v7
	v_exp_f32_e32 v8, v8
	v_exp_f32_e32 v9, v9
	v_add_f32_e32 v6, 1.0, v6
	v_add_f32_e32 v7, 1.0, v7
	v_add_f32_e32 v8, 1.0, v8
	v_add_f32_e32 v9, 1.0, v9
	v_rcp_f32_e32 v6, v6
	v_rcp_f32_e32 v7, v7
	v_rcp_f32_e32 v8, v8
	v_rcp_f32_e32 v9, v9
	v_mul_f32_e32 v6, 0xbf1b4598, v6
	v_mul_f32_e32 v7, 0xbf1b4598, v7
	v_mul_f32_e32 v8, 0xbf1b4598, v8
	v_mul_f32_e32 v9, 0xbf1b4598, v9
	v_mul_f32_e32 v6, 0x3fb8aa3b, v6
	v_mul_f32_e32 v7, 0x3fb8aa3b, v7
	v_mul_f32_e32 v8, 0x3fb8aa3b, v8
	v_mul_f32_e32 v9, 0x3fb8aa3b, v9
	v_exp_f32_e32 v6, v6
	v_exp_f32_e32 v7, v7
	v_exp_f32_e32 v8, v8
	v_exp_f32_e32 v9, v9
	global_store_dwordx4 v[22:23], v[6:9], off
	s_nop 1
	v_mov_b64_e32 v[6:7], v[204:205]
	v_mov_b64_e32 v[8:9], v[206:207]
	s_nop 0
	v_add_f32_e32 v2, v2, v6
	v_add_f32_e32 v3, v3, v7
	v_add_f32_e32 v4, v4, v8
	v_add_f32_e32 v5, v5, v9
	v_mul_f32_e32 v2, 0xbfb8aa3b, v2
	v_mul_f32_e32 v3, 0xbfb8aa3b, v3
	v_mul_f32_e32 v4, 0xbfb8aa3b, v4
	v_mul_f32_e32 v5, 0xbfb8aa3b, v5
	v_exp_f32_e32 v2, v2
	v_exp_f32_e32 v3, v3
	v_exp_f32_e32 v4, v4
	v_exp_f32_e32 v5, v5
	v_add_f32_e32 v2, 1.0, v2
	v_add_f32_e32 v3, 1.0, v3
	v_add_f32_e32 v4, 1.0, v4
	v_add_f32_e32 v5, 1.0, v5
	v_rcp_f32_e32 v2, v2
	v_rcp_f32_e32 v3, v3
	v_rcp_f32_e32 v4, v4
	v_rcp_f32_e32 v5, v5
	v_mul_f32_e32 v2, 0xbf1b4598, v2
	v_mul_f32_e32 v3, 0xbf1b4598, v3
	v_mul_f32_e32 v4, 0xbf1b4598, v4
	v_mul_f32_e32 v5, 0xbf1b4598, v5
	v_mul_f32_e32 v2, 0x3fb8aa3b, v2
	v_mul_f32_e32 v3, 0x3fb8aa3b, v3
	v_mul_f32_e32 v4, 0x3fb8aa3b, v4
	v_mul_f32_e32 v5, 0x3fb8aa3b, v5
	v_exp_f32_e32 v2, v2
	v_exp_f32_e32 v3, v3
	v_exp_f32_e32 v4, v4
	v_exp_f32_e32 v5, v5
	global_store_dwordx4 v[22:23], v[2:5], off offset:64
	s_cbranch_scc1 .LBB0_2759
	s_nop 0
	v_mov_b32_e32 v2, 0
	ds_read_b64 v[2:3], v2 offset:336

.LBB0_2763:
	s_mul_hi_i32 s23, s12, 0x2aaaaaab
	s_lshr_b32 s24, s23, 31
	s_ashr_i32 s23, s23, 3
	s_add_i32 s23, s23, s24
	s_mul_i32 s25, s23, 0xffffe800
	s_lshl_b32 s24, s23, 7
	s_add_i32 s26, s17, s25
	s_ashr_i32 s25, s24, 31
	s_ashr_i32 s27, s26, 31
	v_or_b32_e32 v22, s24, v43
	s_lshl_b64 s[24:25], s[24:25], 7
	v_add_u32_e32 v36, s26, v44
	s_lshl_b64 s[26:27], s[26:27], 8
	s_add_u32 s26, s13, s26
	s_addc_u32 s27, s14, s27
	s_add_u32 s24, s15, s24
	v_lshl_add_u64 v[2:3], s[26:27], 0, v[26:27]
	s_mov_b32 m0, s19
	v_lshl_add_u64 v[4:5], s[26:27], 0, v[28:29]
	s_addc_u32 s25, s16, s25
	v_lshl_add_u64 v[2:3], v[2:3], 0, v[34:35]
	v_lshl_add_u64 v[4:5], v[4:5], 0, v[34:35]
	global_load_lds_dwordx4 v[2:3], off
	v_lshl_add_u64 v[2:3], s[24:25], 0, v[30:31]
	s_mov_b32 m0, s20
	v_lshl_add_u64 v[6:7], s[24:25], 0, v[32:33]
	global_load_lds_dwordx4 v[4:5], off
	v_lshl_add_u64 v[2:3], v[2:3], 0, v[34:35]
	s_mov_b32 m0, s21
	v_lshl_add_u64 v[4:5], v[6:7], 0, v[34:35]
	global_load_lds_dwordx4 v[2:3], off
	s_mov_b32 m0, s22
	v_ashrrev_i32_e32 v23, 31, v22
	global_load_lds_dwordx4 v[4:5], off
	s_waitcnt vmcnt(0)
	s_barrier
	ds_read_b128 v[18:21], v46 offset:17408
	ds_read_b128 v[14:17], v45 offset:1024
	ds_read_b128 v[48:51], v45 offset:2048
	ds_read_b128 v[6:9], v46 offset:18432
	ds_read_b128 v[10:13], v46 offset:19456
	ds_read_b128 v[2:5], v46 offset:20480
	s_waitcnt lgkmcnt(0)
	v_mfma_f32_16x16x32_bf16 v[52:55], v[18:21], v[14:17], 0
	v_lshlrev_b64 v[38:39], 2, v[22:23]
	v_lshl_add_u64 v[40:41], s[2:3], 0, v[38:39]
	global_load_dwordx4 v[200:203], v[40:41], off offset:2048
	global_load_dwordx4 v[204:207], v[40:41], off offset:2112
	v_ashrrev_i32_e32 v37, 31, v36
	v_mfma_f32_16x16x32_bf16 v[56:59], v[10:13], v[14:17], 0
	ds_read_b128 v[14:17], v45 offset:3072
	ds_read_b128 v[60:63], v45 offset:4096
	v_lshlrev_b64 v[88:89], 11, v[36:37]
	v_lshl_add_u64 v[88:89], s[4:5], 0, v[88:89]
	s_waitcnt lgkmcnt(0)
	v_mfma_f32_16x16x32_bf16 v[64:67], v[18:21], v[14:17], 0
	v_lshl_add_u64 v[88:89], v[88:89], 0, v[38:39]
	v_add_u32_e32 v84, 16, v36
	v_ashrrev_i32_e32 v85, 31, v84
	v_mfma_f32_16x16x32_bf16 v[68:71], v[10:13], v[14:17], 0
	ds_read_b128 v[14:17], v45 offset:5120
	ds_read_b128 v[72:75], v45 offset:6144
	v_lshlrev_b64 v[84:85], 11, v[84:85]
	v_lshl_add_u64 v[84:85], s[4:5], 0, v[84:85]
	s_waitcnt lgkmcnt(0)
	v_mfma_f32_16x16x32_bf16 v[76:79], v[18:21], v[14:17], 0
	v_lshl_add_u64 v[84:85], v[84:85], 0, v[38:39]
	v_add_u32_e32 v86, 32, v36
	v_ashrrev_i32_e32 v87, 31, v86
	v_mfma_f32_16x16x32_bf16 v[80:83], v[10:13], v[14:17], 0
	ds_read_b128 v[22:25], v45 offset:7168
	ds_read_b128 v[14:17], v45 offset:8192
	s_waitcnt lgkmcnt(0)
	s_barrier
	v_mfma_f32_16x16x32_bf16 v[52:55], v[6:9], v[48:51], v[52:55]
	v_add_u32_e32 v36, 48, v36
	s_add_i32 s12, s12, s56
	s_add_i32 s17, s17, s18
	v_mfma_f32_16x16x32_bf16 v[48:51], v[2:5], v[48:51], v[56:59]
	s_cmpk_lt_i32 s12, 0xc0
	v_mfma_f32_16x16x32_bf16 v[56:59], v[6:9], v[60:63], v[64:67]
	s_nop 2
	s_waitcnt vmcnt(0)
	s_nop 1
	v_mov_b64_e32 v[64:65], v[200:201]
	v_mov_b64_e32 v[66:67], v[202:203]
	v_mfma_f32_16x16x32_bf16 v[60:63], v[2:5], v[60:63], v[68:71]
	s_nop 0
	v_add_f32_e32 v37, v52, v64
	v_add_f32_e32 v47, v53, v65
	v_add_f32_e32 v52, v54, v66
	v_add_f32_e32 v53, v55, v67
	v_mul_f32_e32 v37, 0xbfb8aa3b, v37
	v_mul_f32_e32 v47, 0xbfb8aa3b, v47
	v_mul_f32_e32 v52, 0xbfb8aa3b, v52
	v_mul_f32_e32 v53, 0xbfb8aa3b, v53
	v_exp_f32_e32 v37, v37
	v_exp_f32_e32 v47, v47
	v_exp_f32_e32 v52, v52
	v_exp_f32_e32 v53, v53
	v_add_f32_e32 v37, 1.0, v37
	v_add_f32_e32 v47, 1.0, v47
	v_add_f32_e32 v52, 1.0, v52
	v_add_f32_e32 v53, 1.0, v53
	v_rcp_f32_e32 v37, v37
	v_rcp_f32_e32 v47, v47
	v_rcp_f32_e32 v52, v52
	v_rcp_f32_e32 v53, v53
	v_mul_f32_e32 v37, 0xbf1b4598, v37
	v_mul_f32_e32 v47, 0xbf1b4598, v47
	v_mul_f32_e32 v52, 0xbf1b4598, v52
	v_mul_f32_e32 v53, 0xbf1b4598, v53
	v_mul_f32_e32 v37, 0x3fb8aa3b, v37
	v_mul_f32_e32 v47, 0x3fb8aa3b, v47
	v_mul_f32_e32 v54, 0x3fb8aa3b, v52
	v_mul_f32_e32 v55, 0x3fb8aa3b, v53
	v_exp_f32_e32 v52, v37
	v_exp_f32_e32 v53, v47
	v_exp_f32_e32 v54, v54
	v_exp_f32_e32 v55, v55
	s_waitcnt lgkmcnt(1)
	v_mfma_f32_16x16x32_bf16 v[18:21], v[18:21], v[22:25], 0
	global_store_dwordx4 v[88:89], v[52:55], off
	s_nop 1
	v_mov_b64_e32 v[52:53], v[204:205]
	v_mov_b64_e32 v[54:55], v[206:207]
	v_mfma_f32_16x16x32_bf16 v[10:13], v[10:13], v[22:25], 0
	s_nop 0
	v_add_f32_e32 v37, v48, v52
	v_add_f32_e32 v47, v49, v53
	v_add_f32_e32 v48, v50, v54
	v_add_f32_e32 v49, v51, v55
	v_mul_f32_e32 v37, 0xbfb8aa3b, v37
	v_mul_f32_e32 v47, 0xbfb8aa3b, v47
	v_mul_f32_e32 v48, 0xbfb8aa3b, v48
	v_mul_f32_e32 v49, 0xbfb8aa3b, v49
	v_exp_f32_e32 v37, v37
	v_exp_f32_e32 v47, v47
	v_exp_f32_e32 v48, v48
	v_exp_f32_e32 v49, v49
	v_add_f32_e32 v37, 1.0, v37
	v_add_f32_e32 v47, 1.0, v47
	v_add_f32_e32 v48, 1.0, v48
	v_add_f32_e32 v49, 1.0, v49
	v_rcp_f32_e32 v37, v37
	v_rcp_f32_e32 v47, v47
	v_rcp_f32_e32 v48, v48
	v_rcp_f32_e32 v49, v49
	v_mul_f32_e32 v37, 0xbf1b4598, v37
	v_mul_f32_e32 v47, 0xbf1b4598, v47
	v_mul_f32_e32 v48, 0xbf1b4598, v48
	v_mul_f32_e32 v49, 0xbf1b4598, v49
	v_mul_f32_e32 v37, 0x3fb8aa3b, v37
	v_mul_f32_e32 v47, 0x3fb8aa3b, v47
	v_mul_f32_e32 v50, 0x3fb8aa3b, v48
	v_mul_f32_e32 v51, 0x3fb8aa3b, v49
	v_exp_f32_e32 v48, v37
	v_exp_f32_e32 v49, v47
	v_exp_f32_e32 v50, v50
	v_exp_f32_e32 v51, v51
	v_lshlrev_b64 v[52:53], 11, v[86:87]
	v_lshl_add_u64 v[52:53], s[4:5], 0, v[52:53]
	global_store_dwordx4 v[88:89], v[48:51], off offset:64
	s_nop 1
	v_mov_b64_e32 v[48:49], v[200:201]
	v_mov_b64_e32 v[50:51], v[202:203]
	s_nop 0
	v_add_f32_e32 v37, v56, v48
	v_add_f32_e32 v47, v57, v49
	v_add_f32_e32 v48, v58, v50
	v_add_f32_e32 v49, v59, v51
	v_mul_f32_e32 v37, 0xbfb8aa3b, v37
	v_mul_f32_e32 v47, 0xbfb8aa3b, v47
	v_mul_f32_e32 v48, 0xbfb8aa3b, v48
	v_mul_f32_e32 v49, 0xbfb8aa3b, v49
	v_exp_f32_e32 v37, v37
	v_exp_f32_e32 v47, v47
	v_exp_f32_e32 v48, v48
	v_exp_f32_e32 v49, v49
	v_add_f32_e32 v37, 1.0, v37
	v_add_f32_e32 v47, 1.0, v47
	v_add_f32_e32 v48, 1.0, v48
	v_add_f32_e32 v49, 1.0, v49
	v_rcp_f32_e32 v37, v37
	v_rcp_f32_e32 v47, v47
	v_rcp_f32_e32 v48, v48
	v_rcp_f32_e32 v49, v49
	v_mul_f32_e32 v37, 0xbf1b4598, v37
	v_mul_f32_e32 v47, 0xbf1b4598, v47
	v_mul_f32_e32 v48, 0xbf1b4598, v48
	v_mul_f32_e32 v49, 0xbf1b4598, v49
	v_mul_f32_e32 v37, 0x3fb8aa3b, v37
	v_mul_f32_e32 v47, 0x3fb8aa3b, v47
	v_mul_f32_e32 v50, 0x3fb8aa3b, v48
	v_mul_f32_e32 v51, 0x3fb8aa3b, v49
	v_exp_f32_e32 v48, v37
	v_exp_f32_e32 v49, v47
	v_exp_f32_e32 v50, v50
	v_exp_f32_e32 v51, v51
	v_lshl_add_u64 v[56:57], v[52:53], 0, v[38:39]
	v_mfma_f32_16x16x32_bf16 v[52:55], v[6:9], v[72:75], v[76:79]
	global_store_dwordx4 v[84:85], v[48:51], off
	s_nop 1
	v_mov_b64_e32 v[48:49], v[204:205]
	v_mov_b64_e32 v[50:51], v[206:207]
	s_waitcnt lgkmcnt(0)
	v_mfma_f32_16x16x32_bf16 v[6:9], v[6:9], v[14:17], v[18:21]
	s_nop 0
	v_add_f32_e32 v37, v60, v48
	v_add_f32_e32 v47, v61, v49
	v_add_f32_e32 v48, v62, v50
	v_add_f32_e32 v49, v63, v51
	v_mul_f32_e32 v37, 0xbfb8aa3b, v37
	v_mul_f32_e32 v47, 0xbfb8aa3b, v47
	v_mul_f32_e32 v48, 0xbfb8aa3b, v48
	v_mul_f32_e32 v49, 0xbfb8aa3b, v49
	v_exp_f32_e32 v37, v37
	v_exp_f32_e32 v47, v47
	v_exp_f32_e32 v48, v48
	v_exp_f32_e32 v49, v49
	v_add_f32_e32 v37, 1.0, v37
	v_add_f32_e32 v47, 1.0, v47
	v_add_f32_e32 v48, 1.0, v48
	v_add_f32_e32 v49, 1.0, v49
	v_rcp_f32_e32 v37, v37
	v_rcp_f32_e32 v47, v47
	v_rcp_f32_e32 v48, v48
	v_rcp_f32_e32 v49, v49
	v_mul_f32_e32 v37, 0xbf1b4598, v37
	v_mul_f32_e32 v47, 0xbf1b4598, v47
	v_mul_f32_e32 v48, 0xbf1b4598, v48
	v_mul_f32_e32 v49, 0xbf1b4598, v49
	v_mul_f32_e32 v37, 0x3fb8aa3b, v37
	v_mul_f32_e32 v47, 0x3fb8aa3b, v47
	v_mul_f32_e32 v50, 0x3fb8aa3b, v48
	v_mul_f32_e32 v51, 0x3fb8aa3b, v49
	v_exp_f32_e32 v48, v37
	v_exp_f32_e32 v49, v47
	v_exp_f32_e32 v50, v50
	v_exp_f32_e32 v51, v51
	global_store_dwordx4 v[84:85], v[48:51], off offset:64
	s_nop 1
	v_mov_b64_e32 v[48:49], v[200:201]
	v_mov_b64_e32 v[50:51], v[202:203]
	s_nop 0
	v_add_f32_e32 v37, v52, v48
	v_add_f32_e32 v47, v53, v49
	v_add_f32_e32 v48, v54, v50
	v_add_f32_e32 v49, v55, v51
	v_mul_f32_e32 v37, 0xbfb8aa3b, v37
	v_mul_f32_e32 v47, 0xbfb8aa3b, v47
	v_mul_f32_e32 v48, 0xbfb8aa3b, v48
	v_mul_f32_e32 v49, 0xbfb8aa3b, v49
	v_exp_f32_e32 v37, v37
	v_exp_f32_e32 v47, v47
	v_exp_f32_e32 v48, v48
	v_exp_f32_e32 v49, v49
	v_add_f32_e32 v37, 1.0, v37
	v_add_f32_e32 v47, 1.0, v47
	v_add_f32_e32 v48, 1.0, v48
	v_add_f32_e32 v49, 1.0, v49
	v_rcp_f32_e32 v37, v37
	v_rcp_f32_e32 v47, v47
	v_rcp_f32_e32 v48, v48
	v_rcp_f32_e32 v49, v49
	v_mul_f32_e32 v37, 0xbf1b4598, v37
	v_mul_f32_e32 v47, 0xbf1b4598, v47
	v_mul_f32_e32 v48, 0xbf1b4598, v48
	v_mul_f32_e32 v49, 0xbf1b4598, v49
	v_mul_f32_e32 v37, 0x3fb8aa3b, v37
	v_mul_f32_e32 v47, 0x3fb8aa3b, v47
	v_mul_f32_e32 v50, 0x3fb8aa3b, v48
	v_mul_f32_e32 v51, 0x3fb8aa3b, v49
	v_exp_f32_e32 v48, v37
	v_exp_f32_e32 v49, v47
	v_exp_f32_e32 v50, v50
	v_exp_f32_e32 v51, v51
	v_mfma_f32_16x16x32_bf16 v[52:55], v[2:5], v[72:75], v[80:83]
	global_store_dwordx4 v[56:57], v[48:51], off
	s_nop 1
	v_mov_b64_e32 v[48:49], v[204:205]
	v_mov_b64_e32 v[50:51], v[206:207]
	v_mfma_f32_16x16x32_bf16 v[2:5], v[2:5], v[14:17], v[10:13]
	s_nop 0
	s_nop 3
	v_add_f32_e32 v37, v52, v48
	v_add_f32_e32 v47, v53, v49
	v_add_f32_e32 v48, v54, v50
	v_add_f32_e32 v49, v55, v51
	v_mul_f32_e32 v37, 0xbfb8aa3b, v37
	v_mul_f32_e32 v47, 0xbfb8aa3b, v47
	v_mul_f32_e32 v48, 0xbfb8aa3b, v48
	v_mul_f32_e32 v49, 0xbfb8aa3b, v49
	v_exp_f32_e32 v37, v37
	v_exp_f32_e32 v47, v47
	v_exp_f32_e32 v48, v48
	v_exp_f32_e32 v49, v49
	v_add_f32_e32 v37, 1.0, v37
	v_add_f32_e32 v47, 1.0, v47
	v_add_f32_e32 v48, 1.0, v48
	v_add_f32_e32 v49, 1.0, v49
	v_rcp_f32_e32 v37, v37
	v_rcp_f32_e32 v47, v47
	v_rcp_f32_e32 v48, v48
	v_rcp_f32_e32 v49, v49
	v_mul_f32_e32 v37, 0xbf1b4598, v37
	v_mul_f32_e32 v47, 0xbf1b4598, v47
	v_mul_f32_e32 v48, 0xbf1b4598, v48
	v_mul_f32_e32 v49, 0xbf1b4598, v49
	v_mul_f32_e32 v37, 0x3fb8aa3b, v37
	v_mul_f32_e32 v47, 0x3fb8aa3b, v47
	v_mul_f32_e32 v50, 0x3fb8aa3b, v48
	v_mul_f32_e32 v51, 0x3fb8aa3b, v49
	v_exp_f32_e32 v48, v37
	v_exp_f32_e32 v49, v47
	v_exp_f32_e32 v50, v50
	v_exp_f32_e32 v51, v51
	v_ashrrev_i32_e32 v37, 31, v36
	v_lshlrev_b64 v[22:23], 11, v[36:37]
	v_lshl_add_u64 v[22:23], s[4:5], 0, v[22:23]
	global_store_dwordx4 v[56:57], v[48:51], off offset:64
	s_nop 1
	v_mov_b64_e32 v[48:49], v[200:201]
	v_mov_b64_e32 v[50:51], v[202:203]
	v_lshl_add_u64 v[22:23], v[22:23], 0, v[38:39]
	s_nop 0
	v_add_f32_e32 v6, v6, v48
	v_add_f32_e32 v7, v7, v49
	v_add_f32_e32 v8, v8, v50
	v_add_f32_e32 v9, v9, v51
	v_mul_f32_e32 v6, 0xbfb8aa3b, v6
	v_mul_f32_e32 v7, 0xbfb8aa3b, v7
	v_mul_f32_e32 v8, 0xbfb8aa3b, v8
	v_mul_f32_e32 v9, 0xbfb8aa3b, v9
	v_exp_f32_e32 v6, v6
	v_exp_f32_e32 v7, v7
	v_exp_f32_e32 v8, v8
	v_exp_f32_e32 v9, v9
	v_add_f32_e32 v6, 1.0, v6
	v_add_f32_e32 v7, 1.0, v7
	v_add_f32_e32 v8, 1.0, v8
	v_add_f32_e32 v9, 1.0, v9
	v_rcp_f32_e32 v6, v6
	v_rcp_f32_e32 v7, v7
	v_rcp_f32_e32 v8, v8
	v_rcp_f32_e32 v9, v9
	v_mul_f32_e32 v6, 0xbf1b4598, v6
	v_mul_f32_e32 v7, 0xbf1b4598, v7
	v_mul_f32_e32 v8, 0xbf1b4598, v8
	v_mul_f32_e32 v9, 0xbf1b4598, v9
	v_mul_f32_e32 v6, 0x3fb8aa3b, v6
	v_mul_f32_e32 v7, 0x3fb8aa3b, v7
	v_mul_f32_e32 v8, 0x3fb8aa3b, v8
	v_mul_f32_e32 v9, 0x3fb8aa3b, v9
	v_exp_f32_e32 v6, v6
	v_exp_f32_e32 v7, v7
	v_exp_f32_e32 v8, v8
	v_exp_f32_e32 v9, v9
	global_store_dwordx4 v[22:23], v[6:9], off
	s_nop 1
	v_mov_b64_e32 v[6:7], v[204:205]
	v_mov_b64_e32 v[8:9], v[206:207]
	s_nop 0
	v_add_f32_e32 v2, v2, v6
	v_add_f32_e32 v3, v3, v7
	v_add_f32_e32 v4, v4, v8
	v_add_f32_e32 v5, v5, v9
	v_mul_f32_e32 v2, 0xbfb8aa3b, v2
	v_mul_f32_e32 v3, 0xbfb8aa3b, v3
	v_mul_f32_e32 v4, 0xbfb8aa3b, v4
	v_mul_f32_e32 v5, 0xbfb8aa3b, v5
	v_exp_f32_e32 v2, v2
	v_exp_f32_e32 v3, v3
	v_exp_f32_e32 v4, v4
	v_exp_f32_e32 v5, v5
	v_add_f32_e32 v2, 1.0, v2
	v_add_f32_e32 v3, 1.0, v3
	v_add_f32_e32 v4, 1.0, v4
	v_add_f32_e32 v5, 1.0, v5
	v_rcp_f32_e32 v2, v2
	v_rcp_f32_e32 v3, v3
	v_rcp_f32_e32 v4, v4
	v_rcp_f32_e32 v5, v5
	v_mul_f32_e32 v2, 0xbf1b4598, v2
	v_mul_f32_e32 v3, 0xbf1b4598, v3
	v_mul_f32_e32 v4, 0xbf1b4598, v4
	v_mul_f32_e32 v5, 0xbf1b4598, v5
	v_mul_f32_e32 v2, 0x3fb8aa3b, v2
	v_mul_f32_e32 v3, 0x3fb8aa3b, v3
	v_mul_f32_e32 v4, 0x3fb8aa3b, v4
	v_mul_f32_e32 v5, 0x3fb8aa3b, v5
	v_exp_f32_e32 v2, v2
	v_exp_f32_e32 v3, v3
	v_exp_f32_e32 v4, v4
	v_exp_f32_e32 v5, v5
	global_store_dwordx4 v[22:23], v[2:5], off offset:64
	s_cbranch_scc1 .LBB0_2763

.LBB0_2766:
	s_mul_hi_i32 s23, s12, 0x2aaaaaab
	s_lshr_b32 s24, s23, 31
	s_ashr_i32 s23, s23, 3
	s_add_i32 s23, s23, s24
	s_mul_i32 s25, s23, 0xffffe800
	s_lshl_b32 s24, s23, 7
	s_add_i32 s26, s17, s25
	s_ashr_i32 s25, s24, 31
	s_ashr_i32 s27, s26, 31
	v_or_b32_e32 v2, s24, v34
	s_lshl_b64 s[24:25], s[24:25], 7
	v_add_u32_e32 v30, s26, v35
	s_lshl_b64 s[26:27], s[26:27], 8
	s_add_u32 s26, s15, s26
	v_ashrrev_i32_e32 v3, 31, v2
	s_addc_u32 s27, s16, s27
	v_lshlrev_b64 v[28:29], 2, v[2:3]
	s_add_u32 s24, s13, s24
	v_lshl_add_u64 v[2:3], s[26:27], 0, v[18:19]
	s_mov_b32 m0, s19
	v_lshl_add_u64 v[4:5], s[26:27], 0, v[20:21]
	s_addc_u32 s25, s14, s25
	v_lshl_add_u64 v[2:3], v[2:3], 0, v[26:27]
	v_lshl_add_u64 v[4:5], v[4:5], 0, v[26:27]
	global_load_lds_dwordx4 v[2:3], off
	v_lshl_add_u64 v[2:3], s[24:25], 0, v[22:23]
	s_mov_b32 m0, s20
	v_lshl_add_u64 v[6:7], s[24:25], 0, v[24:25]
	global_load_lds_dwordx4 v[4:5], off
	v_lshl_add_u64 v[2:3], v[2:3], 0, v[26:27]
	s_mov_b32 m0, s21
	v_lshl_add_u64 v[4:5], v[6:7], 0, v[26:27]
	global_load_lds_dwordx4 v[2:3], off
	s_mov_b32 m0, s22
	v_ashrrev_i32_e32 v31, 31, v30
	global_load_lds_dwordx4 v[4:5], off
	s_waitcnt vmcnt(0)
	s_barrier
	ds_read_b128 v[38:41], v37 offset:17408
	ds_read_b128 v[6:9], v36 offset:1024
	ds_read_b128 v[44:47], v36 offset:2048
	ds_read_b128 v[10:13], v37 offset:18432
	ds_read_b128 v[14:17], v37 offset:19456
	ds_read_b128 v[2:5], v37 offset:20480
	s_waitcnt lgkmcnt(0)
	v_mfma_f32_16x16x32_bf16 v[48:51], v[38:41], v[6:9], 0
	v_lshlrev_b64 v[64:65], 11, v[30:31]
	v_lshl_add_u64 v[80:81], s[4:5], 0, v[64:65]
	v_lshl_add_u64 v[32:33], s[2:3], 0, v[28:29]
	global_load_dwordx4 v[200:203], v[32:33], off
	global_load_dwordx4 v[204:207], v[32:33], off offset:64
	v_mfma_f32_16x16x32_bf16 v[52:55], v[14:17], v[6:9], 0
	ds_read_b128 v[6:9], v36 offset:3072
	ds_read_b128 v[56:59], v36 offset:4096
	ds_read_b128 v[68:71], v36 offset:5120
	ds_read_b128 v[72:75], v36 offset:6144
	v_lshl_add_u64 v[90:91], v[80:81], 0, v[28:29]
	s_waitcnt lgkmcnt(0)
	v_mfma_f32_16x16x32_bf16 v[60:63], v[38:41], v[6:9], 0
	v_add_u32_e32 v88, 16, v30
	v_ashrrev_i32_e32 v89, 31, v88
	s_add_i32 s12, s12, s56
	v_mfma_f32_16x16x32_bf16 v[64:67], v[14:17], v[6:9], 0
	ds_read_b128 v[80:83], v36 offset:7168
	ds_read_b128 v[6:9], v36 offset:8192
	s_waitcnt lgkmcnt(0)
	s_barrier
	s_waitcnt vmcnt(0)
	s_nop 1
	v_mov_b64_e32 v[84:85], v[200:201]
	v_mov_b64_e32 v[86:87], v[202:203]
	v_mfma_f32_16x16x32_bf16 v[48:51], v[10:13], v[44:47], v[48:51]
	s_add_i32 s17, s17, s18
	s_cmpk_lt_i32 s12, 0xc0
	v_mfma_f32_16x16x32_bf16 v[44:47], v[2:5], v[44:47], v[52:55]
	v_mfma_f32_16x16x32_bf16 v[76:79], v[38:41], v[68:71], 0
	s_nop 0
	s_nop 2
	v_add_f32_e32 v31, v48, v84
	v_add_f32_e32 v43, v49, v85
	v_add_f32_e32 v48, v50, v86
	v_add_f32_e32 v49, v51, v87
	v_mul_f32_e32 v31, 0xbfb8aa3b, v31
	v_mul_f32_e32 v43, 0xbfb8aa3b, v43
	v_mul_f32_e32 v48, 0xbfb8aa3b, v48
	v_mul_f32_e32 v49, 0xbfb8aa3b, v49
	v_exp_f32_e32 v31, v31
	v_exp_f32_e32 v43, v43
	v_exp_f32_e32 v48, v48
	v_exp_f32_e32 v49, v49
	v_add_f32_e32 v31, 1.0, v31
	v_add_f32_e32 v43, 1.0, v43
	v_add_f32_e32 v50, 1.0, v48
	v_add_f32_e32 v51, 1.0, v49
	v_rcp_f32_e32 v48, v31
	v_rcp_f32_e32 v49, v43
	v_rcp_f32_e32 v50, v50
	v_rcp_f32_e32 v51, v51
	v_mfma_f32_16x16x32_bf16 v[68:71], v[14:17], v[68:71], 0
	global_store_dwordx4 v[90:91], v[48:51], off
	s_nop 1
	v_mov_b64_e32 v[48:49], v[204:205]
	v_mov_b64_e32 v[50:51], v[206:207]
	s_waitcnt lgkmcnt(1)
	v_mfma_f32_16x16x32_bf16 v[38:41], v[38:41], v[80:83], 0
	s_nop 0
	v_add_f32_e32 v31, v44, v48
	v_add_f32_e32 v43, v45, v49
	v_add_f32_e32 v44, v46, v50
	v_add_f32_e32 v45, v47, v51
	v_mul_f32_e32 v31, 0xbfb8aa3b, v31
	v_mul_f32_e32 v43, 0xbfb8aa3b, v43
	v_mul_f32_e32 v44, 0xbfb8aa3b, v44
	v_mul_f32_e32 v45, 0xbfb8aa3b, v45
	v_exp_f32_e32 v31, v31
	v_exp_f32_e32 v43, v43
	v_exp_f32_e32 v44, v44
	v_exp_f32_e32 v45, v45
	v_add_f32_e32 v31, 1.0, v31
	v_add_f32_e32 v43, 1.0, v43
	v_add_f32_e32 v46, 1.0, v44
	v_add_f32_e32 v47, 1.0, v45
	v_rcp_f32_e32 v44, v31
	v_rcp_f32_e32 v45, v43
	v_rcp_f32_e32 v46, v46
	v_rcp_f32_e32 v47, v47
	v_lshlrev_b64 v[48:49], 11, v[88:89]
	v_lshl_add_u64 v[48:49], s[4:5], 0, v[48:49]
	v_lshl_add_u64 v[52:53], v[48:49], 0, v[28:29]
	global_store_dwordx4 v[90:91], v[44:47], off offset:64
	s_nop 1
	v_mov_b64_e32 v[44:45], v[200:201]
	v_mov_b64_e32 v[46:47], v[202:203]
	v_mfma_f32_16x16x32_bf16 v[48:51], v[10:13], v[56:59], v[60:63]
	v_mfma_f32_16x16x32_bf16 v[14:17], v[14:17], v[80:83], 0
	s_nop 0
	s_nop 5
	v_add_f32_e32 v31, v48, v44
	v_add_f32_e32 v43, v49, v45
	v_add_f32_e32 v44, v50, v46
	v_add_f32_e32 v45, v51, v47
	v_mul_f32_e32 v31, 0xbfb8aa3b, v31
	v_mul_f32_e32 v43, 0xbfb8aa3b, v43
	v_mul_f32_e32 v44, 0xbfb8aa3b, v44
	v_mul_f32_e32 v45, 0xbfb8aa3b, v45
	v_exp_f32_e32 v31, v31
	v_exp_f32_e32 v43, v43
	v_exp_f32_e32 v44, v44
	v_exp_f32_e32 v45, v45
	v_add_f32_e32 v31, 1.0, v31
	v_add_f32_e32 v43, 1.0, v43
	v_add_f32_e32 v46, 1.0, v44
	v_add_f32_e32 v47, 1.0, v45
	v_rcp_f32_e32 v44, v31
	v_rcp_f32_e32 v45, v43
	v_rcp_f32_e32 v46, v46
	v_rcp_f32_e32 v47, v47
	v_mfma_f32_16x16x32_bf16 v[48:51], v[2:5], v[56:59], v[64:67]
	global_store_dwordx4 v[52:53], v[44:47], off
	s_nop 1
	v_mov_b64_e32 v[44:45], v[204:205]
	v_mov_b64_e32 v[46:47], v[206:207]
	s_nop 0
	s_nop 4
	v_add_f32_e32 v31, v48, v44
	v_add_f32_e32 v43, v49, v45
	v_add_f32_e32 v44, v50, v46
	v_add_f32_e32 v45, v51, v47
	v_mul_f32_e32 v31, 0xbfb8aa3b, v31
	v_mul_f32_e32 v43, 0xbfb8aa3b, v43
	v_mul_f32_e32 v44, 0xbfb8aa3b, v44
	v_mul_f32_e32 v45, 0xbfb8aa3b, v45
	v_exp_f32_e32 v31, v31
	v_exp_f32_e32 v43, v43
	v_exp_f32_e32 v44, v44
	v_exp_f32_e32 v45, v45
	v_add_f32_e32 v31, 1.0, v31
	v_add_f32_e32 v43, 1.0, v43
	v_add_f32_e32 v46, 1.0, v44
	v_add_f32_e32 v47, 1.0, v45
	v_rcp_f32_e32 v44, v31
	v_rcp_f32_e32 v45, v43
	v_rcp_f32_e32 v46, v46
	v_rcp_f32_e32 v47, v47
	v_add_u32_e32 v48, 32, v30
	v_ashrrev_i32_e32 v49, 31, v48
	v_lshlrev_b64 v[48:49], 11, v[48:49]
	global_store_dwordx4 v[52:53], v[44:47], off offset:64
	s_nop 1
	v_mov_b64_e32 v[44:45], v[200:201]
	v_mov_b64_e32 v[46:47], v[202:203]
	v_lshl_add_u64 v[48:49], s[4:5], 0, v[48:49]
	v_lshl_add_u64 v[52:53], v[48:49], 0, v[28:29]
	v_mfma_f32_16x16x32_bf16 v[48:51], v[10:13], v[72:75], v[76:79]
	v_add_u32_e32 v30, 48, v30
	s_waitcnt lgkmcnt(0)
	v_mfma_f32_16x16x32_bf16 v[10:13], v[10:13], v[6:9], v[38:41]
	s_nop 0
	s_nop 3
	v_add_f32_e32 v31, v48, v44
	v_add_f32_e32 v43, v49, v45
	v_add_f32_e32 v44, v50, v46
	v_add_f32_e32 v45, v51, v47
	v_mul_f32_e32 v31, 0xbfb8aa3b, v31
	v_mul_f32_e32 v43, 0xbfb8aa3b, v43
	v_mul_f32_e32 v44, 0xbfb8aa3b, v44
	v_mul_f32_e32 v45, 0xbfb8aa3b, v45
	v_exp_f32_e32 v31, v31
	v_exp_f32_e32 v43, v43
	v_exp_f32_e32 v44, v44
	v_exp_f32_e32 v45, v45
	v_add_f32_e32 v31, 1.0, v31
	v_add_f32_e32 v43, 1.0, v43
	v_add_f32_e32 v46, 1.0, v44
	v_add_f32_e32 v47, 1.0, v45
	v_rcp_f32_e32 v44, v31
	v_rcp_f32_e32 v45, v43
	v_rcp_f32_e32 v46, v46
	v_rcp_f32_e32 v47, v47
	v_mfma_f32_16x16x32_bf16 v[48:51], v[2:5], v[72:75], v[68:71]
	global_store_dwordx4 v[52:53], v[44:47], off
	s_nop 1
	v_mov_b64_e32 v[44:45], v[204:205]
	v_mov_b64_e32 v[46:47], v[206:207]
	v_mfma_f32_16x16x32_bf16 v[2:5], v[2:5], v[6:9], v[14:17]
	s_nop 0
	s_nop 3
	v_add_f32_e32 v31, v48, v44
	v_add_f32_e32 v43, v49, v45
	v_add_f32_e32 v44, v50, v46
	v_add_f32_e32 v45, v51, v47
	v_mul_f32_e32 v31, 0xbfb8aa3b, v31
	v_mul_f32_e32 v43, 0xbfb8aa3b, v43
	v_mul_f32_e32 v44, 0xbfb8aa3b, v44
	v_mul_f32_e32 v45, 0xbfb8aa3b, v45
	v_exp_f32_e32 v31, v31
	v_exp_f32_e32 v43, v43
	v_exp_f32_e32 v44, v44
	v_exp_f32_e32 v45, v45
	v_add_f32_e32 v31, 1.0, v31
	v_add_f32_e32 v43, 1.0, v43
	v_add_f32_e32 v46, 1.0, v44
	v_add_f32_e32 v47, 1.0, v45
	v_rcp_f32_e32 v44, v31
	v_rcp_f32_e32 v45, v43
	v_rcp_f32_e32 v46, v46
	v_rcp_f32_e32 v47, v47
	v_ashrrev_i32_e32 v31, 31, v30
	v_lshlrev_b64 v[30:31], 11, v[30:31]
	v_lshl_add_u64 v[30:31], s[4:5], 0, v[30:31]
	global_store_dwordx4 v[52:53], v[44:47], off offset:64
	s_nop 1
	v_mov_b64_e32 v[44:45], v[200:201]
	v_mov_b64_e32 v[46:47], v[202:203]
	v_lshl_add_u64 v[28:29], v[30:31], 0, v[28:29]
	s_nop 0
	v_add_f32_e32 v10, v10, v44
	v_add_f32_e32 v11, v11, v45
	v_add_f32_e32 v12, v12, v46
	v_add_f32_e32 v13, v13, v47
	v_mul_f32_e32 v10, 0xbfb8aa3b, v10
	v_mul_f32_e32 v11, 0xbfb8aa3b, v11
	v_mul_f32_e32 v12, 0xbfb8aa3b, v12
	v_mul_f32_e32 v13, 0xbfb8aa3b, v13
	v_exp_f32_e32 v10, v10
	v_exp_f32_e32 v11, v11
	v_exp_f32_e32 v12, v12
	v_exp_f32_e32 v13, v13
	v_add_f32_e32 v10, 1.0, v10
	v_add_f32_e32 v11, 1.0, v11
	v_add_f32_e32 v12, 1.0, v12
	v_add_f32_e32 v13, 1.0, v13
	v_rcp_f32_e32 v10, v10
	v_rcp_f32_e32 v11, v11
	v_rcp_f32_e32 v12, v12
	v_rcp_f32_e32 v13, v13
	global_store_dwordx4 v[28:29], v[10:13], off
	s_nop 1
	v_mov_b64_e32 v[10:11], v[204:205]
	v_mov_b64_e32 v[12:13], v[206:207]
	s_nop 0
	v_add_f32_e32 v2, v2, v10
	v_add_f32_e32 v3, v3, v11
	v_add_f32_e32 v4, v4, v12
	v_add_f32_e32 v5, v5, v13
	v_mul_f32_e32 v2, 0xbfb8aa3b, v2
	v_mul_f32_e32 v3, 0xbfb8aa3b, v3
	v_mul_f32_e32 v4, 0xbfb8aa3b, v4
	v_mul_f32_e32 v5, 0xbfb8aa3b, v5
	v_exp_f32_e32 v2, v2
	v_exp_f32_e32 v3, v3
	v_exp_f32_e32 v4, v4
	v_exp_f32_e32 v5, v5
	v_add_f32_e32 v2, 1.0, v2
	v_add_f32_e32 v3, 1.0, v3
	v_add_f32_e32 v4, 1.0, v4
	v_add_f32_e32 v5, 1.0, v5
	v_rcp_f32_e32 v2, v2
	v_rcp_f32_e32 v3, v3
	v_rcp_f32_e32 v4, v4
	v_rcp_f32_e32 v5, v5
	global_store_dwordx4 v[28:29], v[2:5], off offset:64
	s_cbranch_scc1 .LBB0_2766
	s_nop 0
	v_mov_b32_e32 v2, 0
	ds_read_b64 v[2:3], v2 offset:352

.LBB0_2770:
	s_mul_hi_i32 s23, s12, 0x2aaaaaab
	s_lshr_b32 s24, s23, 31
	s_ashr_i32 s23, s23, 3
	s_add_i32 s23, s23, s24
	s_mul_i32 s25, s23, 0xffffe800
	s_lshl_b32 s24, s23, 7
	s_add_i32 s26, s17, s25
	s_ashr_i32 s25, s24, 31
	s_ashr_i32 s27, s26, 31
	v_or_b32_e32 v2, s24, v34
	s_lshl_b64 s[24:25], s[24:25], 7
	v_add_u32_e32 v30, s26, v35
	s_lshl_b64 s[26:27], s[26:27], 8
	s_add_u32 s26, s13, s26
	v_ashrrev_i32_e32 v3, 31, v2
	s_addc_u32 s27, s14, s27
	v_lshlrev_b64 v[28:29], 2, v[2:3]
	s_add_u32 s24, s15, s24
	v_lshl_add_u64 v[2:3], s[26:27], 0, v[18:19]
	s_mov_b32 m0, s19
	v_lshl_add_u64 v[4:5], s[26:27], 0, v[20:21]
	s_addc_u32 s25, s16, s25
	v_lshl_add_u64 v[2:3], v[2:3], 0, v[26:27]
	v_lshl_add_u64 v[4:5], v[4:5], 0, v[26:27]
	global_load_lds_dwordx4 v[2:3], off
	v_lshl_add_u64 v[2:3], s[24:25], 0, v[22:23]
	s_mov_b32 m0, s20
	v_lshl_add_u64 v[6:7], s[24:25], 0, v[24:25]
	global_load_lds_dwordx4 v[4:5], off
	v_lshl_add_u64 v[2:3], v[2:3], 0, v[26:27]
	s_mov_b32 m0, s21
	v_lshl_add_u64 v[4:5], v[6:7], 0, v[26:27]
	global_load_lds_dwordx4 v[2:3], off
	s_mov_b32 m0, s22
	v_ashrrev_i32_e32 v31, 31, v30
	global_load_lds_dwordx4 v[4:5], off
	s_waitcnt vmcnt(0)
	s_barrier
	ds_read_b128 v[38:41], v37 offset:17408
	ds_read_b128 v[6:9], v36 offset:1024
	ds_read_b128 v[44:47], v36 offset:2048
	ds_read_b128 v[10:13], v37 offset:18432
	ds_read_b128 v[14:17], v37 offset:19456
	ds_read_b128 v[2:5], v37 offset:20480
	s_waitcnt lgkmcnt(0)
	v_mfma_f32_16x16x32_bf16 v[48:51], v[38:41], v[6:9], 0
	v_lshlrev_b64 v[64:65], 11, v[30:31]
	v_lshl_add_u64 v[80:81], s[4:5], 0, v[64:65]
	v_lshl_add_u64 v[32:33], s[2:3], 0, v[28:29]
	global_load_dwordx4 v[200:203], v[32:33], off offset:2048
	global_load_dwordx4 v[204:207], v[32:33], off offset:2112
	v_mfma_f32_16x16x32_bf16 v[52:55], v[14:17], v[6:9], 0
	ds_read_b128 v[6:9], v36 offset:3072
	ds_read_b128 v[56:59], v36 offset:4096
	ds_read_b128 v[68:71], v36 offset:5120
	ds_read_b128 v[72:75], v36 offset:6144
	v_lshl_add_u64 v[90:91], v[80:81], 0, v[28:29]
	s_waitcnt lgkmcnt(0)
	v_mfma_f32_16x16x32_bf16 v[60:63], v[38:41], v[6:9], 0
	v_add_u32_e32 v88, 16, v30
	v_ashrrev_i32_e32 v89, 31, v88
	s_add_i32 s12, s12, s56
	v_mfma_f32_16x16x32_bf16 v[64:67], v[14:17], v[6:9], 0
	ds_read_b128 v[80:83], v36 offset:7168
	ds_read_b128 v[6:9], v36 offset:8192
	s_waitcnt lgkmcnt(0)
	s_barrier
	s_waitcnt vmcnt(0)
	s_nop 1
	v_mov_b64_e32 v[84:85], v[200:201]
	v_mov_b64_e32 v[86:87], v[202:203]
	v_mfma_f32_16x16x32_bf16 v[48:51], v[10:13], v[44:47], v[48:51]
	s_add_i32 s17, s17, s18
	s_cmpk_lt_i32 s12, 0xc0
	v_mfma_f32_16x16x32_bf16 v[44:47], v[2:5], v[44:47], v[52:55]
	v_mfma_f32_16x16x32_bf16 v[76:79], v[38:41], v[68:71], 0
	s_nop 0
	s_nop 2
	v_add_f32_e32 v31, v48, v84
	v_add_f32_e32 v43, v49, v85
	v_add_f32_e32 v48, v50, v86
	v_add_f32_e32 v49, v51, v87
	v_mul_f32_e32 v31, 0xbfb8aa3b, v31
	v_mul_f32_e32 v43, 0xbfb8aa3b, v43
	v_mul_f32_e32 v48, 0xbfb8aa3b, v48
	v_mul_f32_e32 v49, 0xbfb8aa3b, v49
	v_exp_f32_e32 v31, v31
	v_exp_f32_e32 v43, v43
	v_exp_f32_e32 v48, v48
	v_exp_f32_e32 v49, v49
	v_add_f32_e32 v31, 1.0, v31
	v_add_f32_e32 v43, 1.0, v43
	v_add_f32_e32 v50, 1.0, v48
	v_add_f32_e32 v51, 1.0, v49
	v_rcp_f32_e32 v48, v31
	v_rcp_f32_e32 v49, v43
	v_rcp_f32_e32 v50, v50
	v_rcp_f32_e32 v51, v51
	v_mfma_f32_16x16x32_bf16 v[68:71], v[14:17], v[68:71], 0
	global_store_dwordx4 v[90:91], v[48:51], off
	s_nop 1
	v_mov_b64_e32 v[48:49], v[204:205]
	v_mov_b64_e32 v[50:51], v[206:207]
	s_waitcnt lgkmcnt(1)
	v_mfma_f32_16x16x32_bf16 v[38:41], v[38:41], v[80:83], 0
	s_nop 0
	v_add_f32_e32 v31, v44, v48
	v_add_f32_e32 v43, v45, v49
	v_add_f32_e32 v44, v46, v50
	v_add_f32_e32 v45, v47, v51
	v_mul_f32_e32 v31, 0xbfb8aa3b, v31
	v_mul_f32_e32 v43, 0xbfb8aa3b, v43
	v_mul_f32_e32 v44, 0xbfb8aa3b, v44
	v_mul_f32_e32 v45, 0xbfb8aa3b, v45
	v_exp_f32_e32 v31, v31
	v_exp_f32_e32 v43, v43
	v_exp_f32_e32 v44, v44
	v_exp_f32_e32 v45, v45
	v_add_f32_e32 v31, 1.0, v31
	v_add_f32_e32 v43, 1.0, v43
	v_add_f32_e32 v46, 1.0, v44
	v_add_f32_e32 v47, 1.0, v45
	v_rcp_f32_e32 v44, v31
	v_rcp_f32_e32 v45, v43
	v_rcp_f32_e32 v46, v46
	v_rcp_f32_e32 v47, v47
	v_lshlrev_b64 v[48:49], 11, v[88:89]
	v_lshl_add_u64 v[48:49], s[4:5], 0, v[48:49]
	v_lshl_add_u64 v[52:53], v[48:49], 0, v[28:29]
	global_store_dwordx4 v[90:91], v[44:47], off offset:64
	s_nop 1
	v_mov_b64_e32 v[44:45], v[200:201]
	v_mov_b64_e32 v[46:47], v[202:203]
	v_mfma_f32_16x16x32_bf16 v[48:51], v[10:13], v[56:59], v[60:63]
	v_mfma_f32_16x16x32_bf16 v[14:17], v[14:17], v[80:83], 0
	s_nop 0
	s_nop 5
	v_add_f32_e32 v31, v48, v44
	v_add_f32_e32 v43, v49, v45
	v_add_f32_e32 v44, v50, v46
	v_add_f32_e32 v45, v51, v47
	v_mul_f32_e32 v31, 0xbfb8aa3b, v31
	v_mul_f32_e32 v43, 0xbfb8aa3b, v43
	v_mul_f32_e32 v44, 0xbfb8aa3b, v44
	v_mul_f32_e32 v45, 0xbfb8aa3b, v45
	v_exp_f32_e32 v31, v31
	v_exp_f32_e32 v43, v43
	v_exp_f32_e32 v44, v44
	v_exp_f32_e32 v45, v45
	v_add_f32_e32 v31, 1.0, v31
	v_add_f32_e32 v43, 1.0, v43
	v_add_f32_e32 v46, 1.0, v44
	v_add_f32_e32 v47, 1.0, v45
	v_rcp_f32_e32 v44, v31
	v_rcp_f32_e32 v45, v43
	v_rcp_f32_e32 v46, v46
	v_rcp_f32_e32 v47, v47
	v_mfma_f32_16x16x32_bf16 v[48:51], v[2:5], v[56:59], v[64:67]
	global_store_dwordx4 v[52:53], v[44:47], off
	s_nop 1
	v_mov_b64_e32 v[44:45], v[204:205]
	v_mov_b64_e32 v[46:47], v[206:207]
	s_nop 0
	s_nop 4
	v_add_f32_e32 v31, v48, v44
	v_add_f32_e32 v43, v49, v45
	v_add_f32_e32 v44, v50, v46
	v_add_f32_e32 v45, v51, v47
	v_mul_f32_e32 v31, 0xbfb8aa3b, v31
	v_mul_f32_e32 v43, 0xbfb8aa3b, v43
	v_mul_f32_e32 v44, 0xbfb8aa3b, v44
	v_mul_f32_e32 v45, 0xbfb8aa3b, v45
	v_exp_f32_e32 v31, v31
	v_exp_f32_e32 v43, v43
	v_exp_f32_e32 v44, v44
	v_exp_f32_e32 v45, v45
	v_add_f32_e32 v31, 1.0, v31
	v_add_f32_e32 v43, 1.0, v43
	v_add_f32_e32 v46, 1.0, v44
	v_add_f32_e32 v47, 1.0, v45
	v_rcp_f32_e32 v44, v31
	v_rcp_f32_e32 v45, v43
	v_rcp_f32_e32 v46, v46
	v_rcp_f32_e32 v47, v47
	v_add_u32_e32 v48, 32, v30
	v_ashrrev_i32_e32 v49, 31, v48
	v_lshlrev_b64 v[48:49], 11, v[48:49]
	global_store_dwordx4 v[52:53], v[44:47], off offset:64
	s_nop 1
	v_mov_b64_e32 v[44:45], v[200:201]
	v_mov_b64_e32 v[46:47], v[202:203]
	v_lshl_add_u64 v[48:49], s[4:5], 0, v[48:49]
	v_lshl_add_u64 v[52:53], v[48:49], 0, v[28:29]
	v_mfma_f32_16x16x32_bf16 v[48:51], v[10:13], v[72:75], v[76:79]
	v_add_u32_e32 v30, 48, v30
	s_waitcnt lgkmcnt(0)
	v_mfma_f32_16x16x32_bf16 v[10:13], v[10:13], v[6:9], v[38:41]
	s_nop 0
	s_nop 3
	v_add_f32_e32 v31, v48, v44
	v_add_f32_e32 v43, v49, v45
	v_add_f32_e32 v44, v50, v46
	v_add_f32_e32 v45, v51, v47
	v_mul_f32_e32 v31, 0xbfb8aa3b, v31
	v_mul_f32_e32 v43, 0xbfb8aa3b, v43
	v_mul_f32_e32 v44, 0xbfb8aa3b, v44
	v_mul_f32_e32 v45, 0xbfb8aa3b, v45
	v_exp_f32_e32 v31, v31
	v_exp_f32_e32 v43, v43
	v_exp_f32_e32 v44, v44
	v_exp_f32_e32 v45, v45
	v_add_f32_e32 v31, 1.0, v31
	v_add_f32_e32 v43, 1.0, v43
	v_add_f32_e32 v46, 1.0, v44
	v_add_f32_e32 v47, 1.0, v45
	v_rcp_f32_e32 v44, v31
	v_rcp_f32_e32 v45, v43
	v_rcp_f32_e32 v46, v46
	v_rcp_f32_e32 v47, v47
	v_mfma_f32_16x16x32_bf16 v[48:51], v[2:5], v[72:75], v[68:71]
	global_store_dwordx4 v[52:53], v[44:47], off
	s_nop 1
	v_mov_b64_e32 v[44:45], v[204:205]
	v_mov_b64_e32 v[46:47], v[206:207]
	v_mfma_f32_16x16x32_bf16 v[2:5], v[2:5], v[6:9], v[14:17]
	s_nop 0
	s_nop 3
	v_add_f32_e32 v31, v48, v44
	v_add_f32_e32 v43, v49, v45
	v_add_f32_e32 v44, v50, v46
	v_add_f32_e32 v45, v51, v47
	v_mul_f32_e32 v31, 0xbfb8aa3b, v31
	v_mul_f32_e32 v43, 0xbfb8aa3b, v43
	v_mul_f32_e32 v44, 0xbfb8aa3b, v44
	v_mul_f32_e32 v45, 0xbfb8aa3b, v45
	v_exp_f32_e32 v31, v31
	v_exp_f32_e32 v43, v43
	v_exp_f32_e32 v44, v44
	v_exp_f32_e32 v45, v45
	v_add_f32_e32 v31, 1.0, v31
	v_add_f32_e32 v43, 1.0, v43
	v_add_f32_e32 v46, 1.0, v44
	v_add_f32_e32 v47, 1.0, v45
	v_rcp_f32_e32 v44, v31
	v_rcp_f32_e32 v45, v43
	v_rcp_f32_e32 v46, v46
	v_rcp_f32_e32 v47, v47
	v_ashrrev_i32_e32 v31, 31, v30
	v_lshlrev_b64 v[30:31], 11, v[30:31]
	v_lshl_add_u64 v[30:31], s[4:5], 0, v[30:31]
	global_store_dwordx4 v[52:53], v[44:47], off offset:64
	s_nop 1
	v_mov_b64_e32 v[44:45], v[200:201]
	v_mov_b64_e32 v[46:47], v[202:203]
	v_lshl_add_u64 v[28:29], v[30:31], 0, v[28:29]
	s_nop 0
	v_add_f32_e32 v10, v10, v44
	v_add_f32_e32 v11, v11, v45
	v_add_f32_e32 v12, v12, v46
	v_add_f32_e32 v13, v13, v47
	v_mul_f32_e32 v10, 0xbfb8aa3b, v10
	v_mul_f32_e32 v11, 0xbfb8aa3b, v11
	v_mul_f32_e32 v12, 0xbfb8aa3b, v12
	v_mul_f32_e32 v13, 0xbfb8aa3b, v13
	v_exp_f32_e32 v10, v10
	v_exp_f32_e32 v11, v11
	v_exp_f32_e32 v12, v12
	v_exp_f32_e32 v13, v13
	v_add_f32_e32 v10, 1.0, v10
	v_add_f32_e32 v11, 1.0, v11
	v_add_f32_e32 v12, 1.0, v12
	v_add_f32_e32 v13, 1.0, v13
	v_rcp_f32_e32 v10, v10
	v_rcp_f32_e32 v11, v11
	v_rcp_f32_e32 v12, v12
	v_rcp_f32_e32 v13, v13
	global_store_dwordx4 v[28:29], v[10:13], off
	s_nop 1
	v_mov_b64_e32 v[10:11], v[204:205]
	v_mov_b64_e32 v[12:13], v[206:207]
	s_nop 0
	v_add_f32_e32 v2, v2, v10
	v_add_f32_e32 v3, v3, v11
	v_add_f32_e32 v4, v4, v12
	v_add_f32_e32 v5, v5, v13
	v_mul_f32_e32 v2, 0xbfb8aa3b, v2
	v_mul_f32_e32 v3, 0xbfb8aa3b, v3
	v_mul_f32_e32 v4, 0xbfb8aa3b, v4
	v_mul_f32_e32 v5, 0xbfb8aa3b, v5
	v_exp_f32_e32 v2, v2
	v_exp_f32_e32 v3, v3
	v_exp_f32_e32 v4, v4
	v_exp_f32_e32 v5, v5
	v_add_f32_e32 v2, 1.0, v2
	v_add_f32_e32 v3, 1.0, v3
	v_add_f32_e32 v4, 1.0, v4
	v_add_f32_e32 v5, 1.0, v5
	v_rcp_f32_e32 v2, v2
	v_rcp_f32_e32 v3, v3
	v_rcp_f32_e32 v4, v4
	v_rcp_f32_e32 v5, v5
	global_store_dwordx4 v[28:29], v[2:5], off offset:64
	s_cbranch_scc1 .LBB0_2770
